# slot quota 24 transpose items per wave in layer-0 up-GEMM idle half-round
# baseline (speedup 1.0000x reference)
.LBB0_130:
	s_or_b64 exec, exec, s[0:1]
	s_load_dwordx2 s[0:1], s[92:93], 0x58
	s_load_dwordx2 s[2:3], s[92:93], 0xb8
	s_load_dwordx2 s[4:5], s[92:93], 0xc0
	s_load_dwordx2 s[6:7], s[92:93], 0xc8
	s_load_dwordx2 s[8:9], s[92:93], 0xd0
	s_load_dwordx2 s[10:11], s[92:93], 0xe8
	v_and_b32_e32 v74, 63, v154
	v_lshrrev_b32_e32 v75, 6, v154
	v_mul_u32_u24_e32 v75, 0x2100, v75
	v_lshrrev_b32_e32 v3, 5, v74
	v_and_b32_e32 v4, 31, v74
	v_lshlrev_b32_e32 v4, 2, v4
	v_lshrrev_b32_e32 v5, 3, v74
	v_and_b32_e32 v6, 7, v74
	v_mul_u32_u24_e32 v2, 264, v6
	v_add_u32_e32 v2, v2, v5
	v_lshl_add_u32 v2, v2, 2, v75
	v_lshlrev_b32_e32 v6, 4, v6
	v_mul_u32_u24_e32 v1, 132, v5
	v_add3_u32 v1, v1, v6, v75
	v_readfirstlane_b32 s13, v154
	s_lshr_b32 s13, s13, 6
	s_lshl_b32 s26, s96, 3
	s_add_u32 s13, s13, s26
	s_mov_b32 s12, s13
	s_waitcnt lgkmcnt(0)
	s_cmp_ge_u32 s12, 36352
	s_cbranch_scc1 .Ltra_done
	s_cmp_ge_u32 s12, 33280
	s_cselect_b32 s41, 1, 0
	s_cselect_b32 s26, 33280, 0
	s_sub_u32 s42, s12, s26
	s_cmp_ge_u32 s42, 12288
	s_cbranch_scc1 .Ltra_m2
	s_mul_i32 s43, s42, 43691
	s_lshr_b32 s43, s43, 24
	s_mul_i32 s26, s43, 384
	s_sub_u32 s44, s42, s26
	s_mov_b32 s14, s0
	s_mov_b32 s15, s1
	s_mov_b32 s36, 0xc000
	s_mov_b32 s37, 0x6000000
	s_mov_b32 s38, 0x0
	s_mov_b32 s39, 0x3000000
	s_mov_b32 s40, 0x1000
	s_branch .Ltra_dec_done1

.Ltra_loop:
	s_add_u32 s12, s12, 2048
	s_cmp_lt_u32 s12, 36352
	s_cselect_b32 s24, 1, 0
	s_cbranch_scc0 .Ltra_nonext8
	s_cmp_ge_u32 s12, 33280
	s_cselect_b32 s41, 1, 0
	s_cselect_b32 s26, 33280, 0
	s_sub_u32 s42, s12, s26
	s_cmp_ge_u32 s42, 12288
	s_cbranch_scc1 .Ltra_m11
	s_mul_i32 s43, s42, 43691
	s_lshr_b32 s43, s43, 24
	s_mul_i32 s26, s43, 384
	s_sub_u32 s44, s42, s26
	s_mov_b32 s16, s0
	s_mov_b32 s17, s1
	s_mov_b32 s36, 0xc000
	s_mov_b32 s37, 0x6000000
	s_mov_b32 s38, 0x0
	s_mov_b32 s39, 0x3000000
	s_mov_b32 s40, 0x1000
	s_branch .Ltra_dec_done10

.Ltra_after9:
	ds_write_b32 v1, v10 offset:0
	ds_write_b32 v1, v11 offset:4
	ds_write_b32 v1, v12 offset:8
	ds_write_b32 v1, v13 offset:12
	ds_write_b32 v1, v14 offset:1056
	ds_write_b32 v1, v15 offset:1060
	ds_write_b32 v1, v16 offset:1064
	ds_write_b32 v1, v17 offset:1068
	ds_write_b32 v1, v18 offset:2112
	ds_write_b32 v1, v19 offset:2116
	ds_write_b32 v1, v20 offset:2120
	ds_write_b32 v1, v21 offset:2124
	ds_write_b32 v1, v22 offset:3168
	ds_write_b32 v1, v23 offset:3172
	ds_write_b32 v1, v24 offset:3176
	ds_write_b32 v1, v25 offset:3180
	ds_write_b32 v1, v26 offset:4224
	ds_write_b32 v1, v27 offset:4228
	ds_write_b32 v1, v28 offset:4232
	ds_write_b32 v1, v29 offset:4236
	ds_write_b32 v1, v30 offset:5280
	ds_write_b32 v1, v31 offset:5284
	ds_write_b32 v1, v32 offset:5288
	ds_write_b32 v1, v33 offset:5292
	ds_write_b32 v1, v34 offset:6336
	ds_write_b32 v1, v35 offset:6340
	ds_write_b32 v1, v36 offset:6344
	ds_write_b32 v1, v37 offset:6348
	ds_write_b32 v1, v38 offset:7392
	ds_write_b32 v1, v39 offset:7396
	ds_write_b32 v1, v40 offset:7400
	ds_write_b32 v1, v41 offset:7404
	v_mad_u32_u24 v9, v5, s22, v6
	s_lshl_b32 s46, s22, 3
	s_waitcnt lgkmcnt(0)
	ds_read_b32 v74, v2 offset:0
	ds_read_b32 v75, v2 offset:132
	ds_read_b32 v76, v2 offset:264
	ds_read_b32 v77, v2 offset:396
	ds_read_b32 v78, v2 offset:528
	ds_read_b32 v79, v2 offset:660
	ds_read_b32 v80, v2 offset:792
	ds_read_b32 v81, v2 offset:924
	ds_read_b32 v82, v2 offset:32
	ds_read_b32 v83, v2 offset:164
	ds_read_b32 v84, v2 offset:296
	ds_read_b32 v85, v2 offset:428
	ds_read_b32 v86, v2 offset:560
	ds_read_b32 v87, v2 offset:692
	ds_read_b32 v88, v2 offset:824
	ds_read_b32 v89, v2 offset:956
	s_waitcnt lgkmcnt(8)
	v_cvt_pk_bf16_f32 v106, v74, v75
	v_cvt_pk_bf16_f32 v107, v76, v77
	v_cvt_pk_bf16_f32 v108, v78, v79
	v_cvt_pk_bf16_f32 v109, v80, v81
	global_store_dwordx4 v9, v[106:109], s[18:19]
	s_add_u32 s18, s18, s46
	s_addc_u32 s19, s19, 0
	ds_read_b32 v90, v2 offset:64
	ds_read_b32 v91, v2 offset:196
	ds_read_b32 v92, v2 offset:328
	ds_read_b32 v93, v2 offset:460
	ds_read_b32 v94, v2 offset:592
	ds_read_b32 v95, v2 offset:724
	ds_read_b32 v96, v2 offset:856
	ds_read_b32 v97, v2 offset:988
	s_waitcnt lgkmcnt(8)
	v_cvt_pk_bf16_f32 v110, v82, v83
	v_cvt_pk_bf16_f32 v111, v84, v85
	v_cvt_pk_bf16_f32 v112, v86, v87
	v_cvt_pk_bf16_f32 v113, v88, v89
	global_store_dwordx4 v9, v[110:113], s[18:19]
	s_add_u32 s18, s18, s46
	s_addc_u32 s19, s19, 0
	ds_read_b32 v98, v2 offset:96
	ds_read_b32 v99, v2 offset:228
	ds_read_b32 v100, v2 offset:360
	ds_read_b32 v101, v2 offset:492
	ds_read_b32 v102, v2 offset:624
	ds_read_b32 v103, v2 offset:756
	ds_read_b32 v104, v2 offset:888
	ds_read_b32 v105, v2 offset:1020
	s_waitcnt lgkmcnt(8)
	v_cvt_pk_bf16_f32 v106, v90, v91
	v_cvt_pk_bf16_f32 v107, v92, v93
	v_cvt_pk_bf16_f32 v108, v94, v95
	v_cvt_pk_bf16_f32 v109, v96, v97
	global_store_dwordx4 v9, v[106:109], s[18:19]
	s_add_u32 s18, s18, s46
	s_addc_u32 s19, s19, 0
	s_waitcnt lgkmcnt(0)
	v_cvt_pk_bf16_f32 v110, v98, v99
	v_cvt_pk_bf16_f32 v111, v100, v101
	v_cvt_pk_bf16_f32 v112, v102, v103
	v_cvt_pk_bf16_f32 v113, v104, v105
	global_store_dwordx4 v9, v[110:113], s[18:19]
	s_cmp_eq_u32 s24, 0
	s_cbranch_scc1 .Ltra_done
	s_add_u32 s12, s12, 2048
	s_cmp_lt_u32 s12, 36352
	s_cselect_b32 s24, 1, 0
	s_cbranch_scc0 .Ltra_nonext17
	s_cmp_ge_u32 s12, 33280
	s_cselect_b32 s41, 1, 0
	s_cselect_b32 s26, 33280, 0
	s_sub_u32 s42, s12, s26
	s_cmp_ge_u32 s42, 12288
	s_cbranch_scc1 .Ltra_m20
	s_mul_i32 s43, s42, 43691
	s_lshr_b32 s43, s43, 24
	s_mul_i32 s26, s43, 384
	s_sub_u32 s44, s42, s26
	s_mov_b32 s14, s0
	s_mov_b32 s15, s1
	s_mov_b32 s36, 0xc000
	s_mov_b32 s37, 0x6000000
	s_mov_b32 s38, 0x0
	s_mov_b32 s39, 0x3000000
	s_mov_b32 s40, 0x1000
	s_branch .Ltra_dec_done19

.LBB0_1179:
	s_waitcnt vmcnt(0)
	s_barrier
	s_cmp_lt_u32 s96, 128
	s_cbranch_scc1 .LBB0_1180
	s_load_dwordx2 s[0:1], s[92:93], 0x58
	s_load_dwordx2 s[2:3], s[92:93], 0xb8
	s_load_dwordx2 s[4:5], s[92:93], 0xc0
	s_load_dwordx2 s[6:7], s[92:93], 0xc8
	s_load_dwordx2 s[8:9], s[92:93], 0xd0
	s_load_dwordx2 s[10:11], s[92:93], 0xe8
	v_and_b32_e32 v74, 63, v154
	v_lshrrev_b32_e32 v75, 6, v154
	v_mul_u32_u24_e32 v75, 0x2100, v75
	v_lshrrev_b32_e32 v3, 5, v74
	v_and_b32_e32 v4, 31, v74
	v_lshlrev_b32_e32 v4, 2, v4
	v_lshrrev_b32_e32 v5, 3, v74
	v_and_b32_e32 v6, 7, v74
	v_mul_u32_u24_e32 v2, 264, v6
	v_add_u32_e32 v2, v2, v5
	v_lshl_add_u32 v2, v2, 2, v75
	v_lshlrev_b32_e32 v6, 4, v6
	v_mul_u32_u24_e32 v1, 132, v5
	v_add3_u32 v1, v1, v6, v75
	v_readfirstlane_b32 s13, v154
	s_lshr_b32 s13, s13, 6
	s_lshl_b32 s26, s96, 3
	s_add_u32 s13, s13, s26
	s_sub_u32 s12, s13, 1024
	s_add_u32 s12, s12, 36352
	s_waitcnt lgkmcnt(0)
	s_cmp_ge_u32 s12, 60928
	s_cbranch_scc1 .Ltrs_done
	s_cmp_ge_u32 s12, 33280
	s_cselect_b32 s41, 1, 0
	s_cselect_b32 s26, 33280, 0
	s_sub_u32 s42, s12, s26
	s_cmp_ge_u32 s42, 12288
	s_cbranch_scc1 .Ltrs_m2
	s_mul_i32 s43, s42, 43691
	s_lshr_b32 s43, s43, 24
	s_mul_i32 s26, s43, 384
	s_sub_u32 s44, s42, s26
	s_mov_b32 s14, s0
	s_mov_b32 s15, s1
	s_mov_b32 s36, 0xc000
	s_mov_b32 s37, 0x6000000
	s_mov_b32 s38, 0x0
	s_mov_b32 s39, 0x3000000
	s_mov_b32 s40, 0x1000
	s_branch .Ltrs_dec_done1
